# final RMSNorm rows remapped to the workgroup's own row-panel group; FF2(L1)->final seam synchronises only that 4-workgroup group
# speedup vs baseline: 1.0129x; 1.0129x over previous
; __device__ __forceinline__ int lane_id() { int l; asm volatile("v_mbcnt_lo_u32_b32 %0, -1, 0\n\tv_mbcnt_hi_u32_b32 %0, -1, %0" : "=v"(l)); return l; }
; #define LAS __attribute__((address_space(3)))
; __device__ __forceinline__ void xb_add_l2(unsigned* p, unsigned v) { (void)__hip_atomic_fetch_add(p, v, __ATOMIC_RELAXED, __HIP_MEMORY_SCOPE_WORKGROUP); }
; __device__ __forceinline__ unsigned xb_ld_l2(unsigned* p) { unsigned v; const unsigned z = 0u; asm volatile("global_atomic_add %0, %1, %2, off sc0\n\ts_waitcnt vmcnt(0)" : "=v"(v) : "v"(p), "v"(z) : "memory"); return v; }
; __device__ __forceinline__ unsigned xb_xcc_id() { return (unsigned)__builtin_amdgcn_s_getreg((3 << 11) | 20) & 0xFu; }
; #define XB_SPIN(cond, bar) do { unsigned _sp = 0; while (cond) { __builtin_amdgcn_s_sleep(1); \
;     if ((++_sp & 255u) == 0u) { if (xb_ld(&(bar)[XB_TMO])) break; if (_sp > XB_SPIN_CAP) { atomicAdd(&(bar)[XB_TMO], 1u); break; } } } } while (0)
; __device__ __forceinline__ void xcd_local_barrier(unsigned* bar, volatile LAS unsigned* st, int wid0) {
;     asm volatile("s_waitcnt vmcnt(0)" ::: "memory");
;     __syncthreads();
;     if (wid0 == 0 && lane_id() == 0) {
;         unsigned zo = 0; asm volatile("" : "+s"(zo));
;         unsigned* cnt = bar + zo + XB_LCNT2(xb_xcc_id());
;         const unsigned e = st[6] + 1u; st[6] = e; const unsigned target = e * st[4];
;         xb_add_l2(cnt, 1u);
;         XB_SPIN(xb_ld_l2(cnt) < target, bar);
;         __builtin_amdgcn_fence(__ATOMIC_ACQUIRE, "agent");
;         asm volatile("s_waitcnt vmcnt(0)" ::: "memory");
;     }
;     __syncthreads();
.LBB13_2170:
	s_cmp_gt_i32 s89, 16
	s_cselect_b64 s[2:3], -1, 0
	s_and_b64 s[0:1], s[0:1], s[2:3]
	s_andn2_b64 vcc, exec, s[0:1]
	s_cbranch_vccnz .LBB13_2250
	s_load_dword s4, s[86:87], 0xb8
	s_load_dwordx2 s[0:1], s[86:87], 0xa8
	s_getreg_b32 s22, hwreg(HW_REG_XCC_ID, 0, 4)
	s_waitcnt lgkmcnt(0)
	s_mulk_i32 s4, 0xd80
	s_ashr_i32 s5, s4, 31
	s_lshl_b64 s[4:5], s[4:5], 2
	s_add_u32 s0, s0, s4
	s_addc_u32 s1, s1, s5
	s_add_u32 s4, s0, 0x4000
	s_addc_u32 s5, s1, 0
	s_add_i32 s0, 0, 0x2117c
	s_waitcnt vmcnt(0)
	v_mov_b32_e32 v0, s0
	ds_read_b32 v0, v0
	s_waitcnt lgkmcnt(0)
	v_readfirstlane_b32 s0, v0
	s_cmp_eq_u32 s0, 0
	s_cbranch_scc1 .LBB13_2186
	s_waitcnt vmcnt(0)
	v_readlane_b32 s0, v238, 10
	v_readlane_b32 s1, v238, 11
	s_and_b64 vcc, exec, s[0:1]
	s_barrier
	s_cbranch_vccnz .LBB13_2193
	v_mbcnt_lo_u32_b32 v0, -1, 0
	v_mbcnt_hi_u32_b32 v0, -1, v0
	s_mov_b32 s9, 0
	v_cmp_eq_u32_e32 vcc, 0, v0
	s_and_saveexec_b64 s[0:1], vcc
	s_cbranch_execz .LBB13_2192
	s_mov_b32 s8, 0
	s_lshl_b64 s[8:9], s[8:9], 2
	s_add_u32 s8, s4, s8
	s_getreg_b32 s10, hwreg(HW_REG_XCC_ID, 0, 4)
	s_addc_u32 s9, s5, s9
	s_lshl_b32 s10, s10, 8
	s_and_b32 s10, s10, 0xf00
	s_add_u32 s8, s8, s10
	s_addc_u32 s9, s9, 0
	s_add_u32 s8, s8, 0xc200
	s_addc_u32 s9, s9, 0
	s_add_i32 s10, 0, 0x2116c
	v_mov_b32_e32 v1, s10
	ds_read_b32 v0, v1
	s_add_i32 s10, 0, 0x21170
	s_mov_b64 s[6:7], exec
	v_mbcnt_lo_u32_b32 v2, s6, 0
	v_mbcnt_hi_u32_b32 v2, s7, v2
	s_waitcnt lgkmcnt(0)
	v_and_b32_e32 v0, 7, v0
	v_lshlrev_b32_e32 v6, 12, v0
	v_mov_b32_e32 v1, s10
	ds_read_b32 v1, v1
	s_mov_b32 s23, 1
	v_cmp_eq_u32_e32 vcc, 0, v2
	s_and_saveexec_b64 s[10:11], vcc
	s_cbranch_execz .LBB13_2176
	s_bcnt1_i32_b64 s6, s[6:7]
	v_mov_b32_e32 v2, 0
	v_mov_b32_e32 v3, s6
	global_atomic_add v6, v3, s[8:9]
.LBB13_2176:
	s_or_b64 exec, exec, s[10:11]
	s_waitcnt lgkmcnt(0)
	v_lshrrev_b32_e32 v1, 3, v1
	v_mul_u32_u24_e32 v2, 5, v1
	s_mov_b64 s[6:7], 0
	v_mov_b32_e32 v3, 0
	v_mov_b32_e32 v7, 0
	v_mov_b64_e32 v[0:1], s[8:9]
	s_nop 0
	v_lshl_add_u64 v[0:1], v[0:1], 0, v[6:7]
	s_branch .LBB13_2179

; __device__ __forceinline__ int lane_id() { int l; asm volatile("v_mbcnt_lo_u32_b32 %0, -1, 0\n\tv_mbcnt_hi_u32_b32 %0, -1, %0" : "=v"(l)); return l; }
; __device__ __forceinline__ float hsq4(const f32x4& a) { return (a[0] * a[0] + a[1] * a[1]) + (a[2] * a[2] + a[3] * a[3]); }
; __device__ __forceinline__ void phase_final(int wid0, const pg8::Place& pl, const float* g, const bf16_t* xb, float* dst) {
;     int tid_ = wid0 * 64 + lane_id(); asm volatile("" : "+v"(tid_));
;     const int lane = tid_ & 63, wave = tid_ >> 6, nr = T / pl.nx, r0 = pl.jx * nr;
;     for (int lr = pl.rank * NWAVES + wave; lr < nr; lr += pl.nloc * NWAVES) { const int row = r0 + lr;
;         const pg8::u32x2* xr = (const pg8::u32x2*)(xb + (size_t)row * (2 * DM) + DM); f32x4* yr = (f32x4*)(dst + (size_t)row * DM); f32x4 v[4]; float s = 0.f;
; #pragma unroll
;         for (int j = 0; j < 4; ++j) { const pg8::u32x2 w = xr[lane + 64 * j];
;             v[j][0] = __uint_as_float(w.x << 16); v[j][1] = __uint_as_float(w.x & 0xffff0000u); v[j][2] = __uint_as_float(w.y << 16); v[j][3] = __uint_as_float(w.y & 0xffff0000u); s += pg8::hsq4(v[j]); }
;         const float rstd = rsqrtf(wsum(s) * (1.f / DM) + EPS);
; #pragma unroll
;         for (int j = 0; j < 4; ++j) yr[lane + 64 * j] = v[j] * rstd * *(const f32x4*)(g + 4 * (lane + 64 * j)); }
.LBB13_2249:
.LBB13_2250:
	s_cmp_gt_i32 s88, 16
	s_cselect_b64 s[0:1], -1, 0
	s_xor_b64 s[2:3], s[2:3], -1
	s_or_b64 s[0:1], s[0:1], s[2:3]
	s_and_b64 vcc, exec, s[0:1]
	s_cbranch_vccnz .LBB13_2254
	s_add_i32 s0, 0, 0x21168
	s_waitcnt vmcnt(0)
	v_mov_b32_e32 v0, s0
	s_add_i32 s0, 0, 0x2116c
	v_mov_b32_e32 v1, s0
	s_add_i32 s0, 0, 0x21170
	s_waitcnt lgkmcnt(0)
	v_mov_b32_e32 v2, s0
	s_add_i32 s0, 0, 0x21174
	s_mov_b32 s2, 0
	v_mov_b32_e32 v3, s0
	ds_read_b32 v0, v0
	ds_read_b32 v1, v1
	ds_read_b32 v2, v2
	ds_read_b32 v3, v3
	v_readlane_b32 s6, v238, 2
	s_waitcnt lgkmcnt(3)
	v_readfirstlane_b32 s1, v0
	s_waitcnt lgkmcnt(2)
	v_readfirstlane_b32 s5, v1
	v_mbcnt_lo_u32_b32 v0, -1, 0
	v_mbcnt_hi_u32_b32 v0, -1, v0
	s_waitcnt lgkmcnt(0)
	v_readfirstlane_b32 s3, v3
	s_abs_i32 s4, s3
	v_cvt_f32_u32_e32 v3, s4
	v_add_u32_e32 v0, s6, v0
	s_sub_i32 s6, 0, s4
	s_ashr_i32 s3, s3, 31
	v_rcp_iflag_f32_e32 v1, v3
	v_readfirstlane_b32 s0, v2
	v_ashrrev_i32_e32 v8, 6, v0
	v_mul_f32_e32 v1, 0x4f7ffffe, v1
	v_cvt_u32_f32_e32 v1, v1
	s_nop 0
	v_readfirstlane_b32 s7, v1
	s_mul_i32 s6, s6, s7
	s_mul_hi_u32 s6, s7, s6
	s_add_i32 s7, s7, s6
	s_lshr_b32 s6, s7, 17
	s_mul_i32 s7, s6, s4
	s_sub_i32 s7, 0x8000, s7
	s_add_i32 s8, s6, 1
	s_sub_i32 s9, s7, s4
	s_cmp_ge_u32 s7, s4
	s_cselect_b32 s6, s8, s6
	s_cselect_b32 s7, s9, s7
	s_add_i32 s8, s6, 1
	s_cmp_ge_u32 s7, s4
	s_cselect_b32 s4, s8, s6
	s_xor_b32 s4, s4, s3
	s_sub_i32 s8, s4, s3
	s_and_b32 s9, s5, 7
	s_lshr_b32 s10, s5, 4
	s_lshl_b32 s10, s10, 3
	s_add_i32 s9, s9, s10
	s_lshl_b32 s9, s9, 8
	s_bfe_u32 s10, s5, 0x10003
	s_lshl_b32 s10, s10, 7
	s_add_i32 s4, s9, s10
	v_add_u32_e32 v12, s4, v8
	v_cmp_gt_i32_e32 vcc, s8, v12
	s_and_saveexec_b64 s[6:7], vcc
	s_cbranch_execz .LBB13_2254
	s_ashr_i32 s3, s2, 31
	s_lshl_b64 s[6:7], s[2:3], 3
	s_add_u32 s6, s86, s6
	s_mul_i32 s1, s8, s1
	s_add_i32 s8, s4, 0x80
	s_addc_u32 s7, s87, s7
	s_load_dwordx2 s[10:11], s[86:87], 0xa0
	s_load_dwordx2 s[12:13], s[6:7], 0x98
	s_add_i32 s4, s4, s1
	v_add_u32_e32 v8, s4, v8
	v_and_b32_e32 v13, 63, v0
	v_ashrrev_i32_e32 v9, 31, v8
	v_lshlrev_b32_e32 v10, 4, v13
	v_mov_b32_e32 v11, 0
	s_mov_b32 s0, 8
	v_lshlrev_b64 v[14:15], 12, v[8:9]
	v_or_b32_e32 v2, 0x400, v10
	v_mov_b32_e32 v3, v11
	v_or_b32_e32 v4, 0x800, v10
	v_mov_b32_e32 v5, v11
	v_or_b32_e32 v6, 0xc00, v10
	v_mov_b32_e32 v7, v11
	v_lshl_or_b32 v8, v13, 3, v14
	v_mov_b32_e32 v9, v15
	s_ashr_i32 s1, s0, 31
	v_or_b32_e32 v14, v14, v10
	s_waitcnt lgkmcnt(0)
	v_lshl_add_u64 v[0:1], s[12:13], 0, v[10:11]
	v_lshl_add_u64 v[2:3], s[12:13], 0, v[2:3]
	v_lshl_add_u64 v[4:5], s[12:13], 0, v[4:5]
	v_lshl_add_u64 v[6:7], s[12:13], 0, v[6:7]
	s_lshl_b64 s[2:3], s[2:3], 2
	v_lshl_add_u64 v[8:9], s[10:11], 0, v[8:9]
	s_lshl_b64 s[4:5], s[0:1], 12
	v_lshl_add_u64 v[10:11], s[10:11], 0, v[14:15]
	s_mov_b64 s[6:7], 0
	v_mov_b32_e32 v13, 0x358637bd
	s_mov_b32 s1, 0x800000
